# hand-written GDN input prep loop in hyb_prep phase (conv+silu+l2norm+gates): batched 16B loads, weights resident in VGPRs, 16-lane DPP norms
# speedup vs baseline: 1.1788x; 1.0255x over previous
; __device__ __forceinline__ float bf2f(bf16_t h) { return __uint_as_float(((unsigned)h) << 16); }
; __device__ __forceinline__ float siluf_(float x) { return x * __builtin_amdgcn_rcpf(1.f + __expf(-x)); }
; __device__ __forceinline__ void hyb_prep_phase(const Params& p, float* sm, int bid, int nb) {
;     ...
;   for (int row = bid * 4 + wave; row < R; row += nb * 4) {
;     const int pr = row % LP;
;     if (pr < PADR) continue;
;     float y[12][2];
; #pragma unroll
;     for (int g = 0; g < 12; g++) {
;       const int c = g * 128 + lane * 2;
;       float y0 = 0.f, y1 = 0.f;
; #pragma unroll
;       for (int j = 0; j < 4; j++) {
;         const unsigned u = *(const unsigned*)(z + (size_t)(row - 3 + j) * ZLD + 1536 + c);
;         const float2 w = *(const float2*)(p.hyb_conv + j * 1536 + c);
;         y0 += w.x * bf2f((bf16_t)(u & 0xffff));
;         y1 += w.y * bf2f((bf16_t)(u >> 16));
;       }
;       y[g][0] = siluf_(y0); y[g][1] = siluf_(y1);
.LBB0_2172:
	s_or_b64 exec, exec, s[0:1]
	s_mov_b32 s0, 0x8200
	v_cmp_gt_i32_e32 vcc, s0, v10
	s_and_saveexec_b64 s[26:27], vcc
	s_cbranch_execz .LBB0_2180
	v_readfirstlane_b32 s4, v10
	v_readlane_b32 s8, v247, 3
	v_readlane_b32 s9, v247, 4
	v_readlane_b32 s10, v247, 1
	v_readlane_b32 s11, v247, 2
	s_add_u32 s12, s8, 0x19980000
	s_addc_u32 s13, s9, 0
	s_add_u32 s14, s8, 0x19c8c000
	s_addc_u32 s15, s9, 0
	s_add_u32 s8, s8, 0xb600000
	s_addc_u32 s9, s9, 0
	s_lshl_b32 s16, s39, 2
	s_mov_b32 s18, 0xbfb8aa3b
	s_mov_b32 s19, 0xbfb8aa3b
	s_mov_b32 s20, 1.0
	s_mov_b32 s21, 1.0
	v_lshlrev_b32_e32 v167, 5, v78
	v_add_u32_e32 v204, 0x0, v167
	s_nop 0
	global_load_dwordx4 v[100:103], v204, s[60:61]
	global_load_dwordx4 v[104:107], v204, s[60:61] offset:16
	v_add_u32_e32 v204, 0x1800, v167
	s_nop 0
	global_load_dwordx4 v[108:111], v204, s[60:61]
	global_load_dwordx4 v[112:115], v204, s[60:61] offset:16
	v_add_u32_e32 v204, 0x3000, v167
	s_nop 0
	global_load_dwordx4 v[116:119], v204, s[60:61]
	global_load_dwordx4 v[120:123], v204, s[60:61] offset:16
	v_add_u32_e32 v204, 0x4800, v167
	s_nop 0
	global_load_dwordx4 v[124:127], v204, s[60:61]
	global_load_dwordx4 v[128:131], v204, s[60:61] offset:16
	v_add_u32_e32 v204, 0x800, v167
	s_nop 0
	global_load_dwordx4 v[132:135], v204, s[60:61]
	global_load_dwordx4 v[136:139], v204, s[60:61] offset:16
	v_add_u32_e32 v204, 0x2000, v167
	s_nop 0
	global_load_dwordx4 v[140:143], v204, s[60:61]
	global_load_dwordx4 v[144:147], v204, s[60:61] offset:16
	v_add_u32_e32 v204, 0x3800, v167
	s_nop 0
	global_load_dwordx4 v[148:151], v204, s[60:61]
	global_load_dwordx4 v[152:155], v204, s[60:61] offset:16
	v_add_u32_e32 v204, 0x5000, v167
	s_nop 0
	global_load_dwordx4 v[156:159], v204, s[60:61]
	global_load_dwordx4 v[168:171], v204, s[60:61] offset:16
	v_add_u32_e32 v204, 0x1000, v167
	s_nop 0
	global_load_dwordx4 v[172:175], v204, s[60:61]
	global_load_dwordx4 v[176:179], v204, s[60:61] offset:16
	v_add_u32_e32 v204, 0x2800, v167
	s_nop 0
	global_load_dwordx4 v[180:183], v204, s[60:61]
	global_load_dwordx4 v[184:187], v204, s[60:61] offset:16
	v_add_u32_e32 v204, 0x4000, v167
	s_nop 0
	global_load_dwordx4 v[188:191], v204, s[60:61]
	global_load_dwordx4 v[192:195], v204, s[60:61] offset:16
	v_add_u32_e32 v204, 0x5800, v167
	s_nop 0
	global_load_dwordx4 v[196:199], v204, s[60:61]
	global_load_dwordx4 v[200:203], v204, s[60:61] offset:16
	v_and_b32_e32 v205, 3, v78
	v_lshlrev_b32_e32 v205, 2, v205
	global_load_dword v165, v205, s[64:65]
	global_load_dword v166, v205, s[62:63]
	v_lshlrev_b32_e32 v8, 4, v78
	s_waitcnt vmcnt(0)
	v_mul_f32_e32 v166, 0x3fb8aa3b, v166
	v_exp_f32_e32 v166, v166
	s_nop 1
	v_sub_f32_e32 v166, 0, v166
.Lp5_row:
	s_mov_b32 s5, s4
	s_cmp_ge_u32 s5, 0x2080
	s_cselect_b32 s6, 0x2080, 0
	s_sub_u32 s5, s5, s6
	s_cmp_ge_u32 s5, 0x2080
	s_cselect_b32 s6, 0x2080, 0
	s_sub_u32 s5, s5, s6
	s_cmp_ge_u32 s5, 0x2080
	s_cselect_b32 s6, 0x2080, 0
	s_sub_u32 s5, s5, s6
	s_cmp_lt_u32 s5, 0x70
	s_cbranch_scc1 .Lp5_next
	s_lshl_b32 s7, s4, 6
	v_add_u32_e32 v11, s7, v205
	s_mul_i32 s6, s4, 0x1c00
	s_add_u32 s6, s6, 0xffffb800
	global_load_dword v160, v11, s[12:13] offset:32
	global_load_dword v161, v11, s[12:13] offset:48
	v_add_u32_e32 v96, s6, v8
	v_add_u32_e32 v97, 0x1c00, v96
	v_add_u32_e32 v98, 0x3800, v96
	v_add_u32_e32 v99, 0x5400, v96
	global_load_dwordx4 v[48:51], v96, s[8:9]
	global_load_dwordx4 v[52:55], v97, s[8:9]
	global_load_dwordx4 v[56:59], v98, s[8:9]
	global_load_dwordx4 v[60:63], v99, s[8:9]
	global_load_dwordx4 v[64:67], v96, s[8:9] offset:1024
	global_load_dwordx4 v[68:71], v97, s[8:9] offset:1024
	global_load_dwordx4 v[72:75], v98, s[8:9] offset:1024
	global_load_dwordx4 v[76:79], v99, s[8:9] offset:1024
	global_load_dwordx4 v[80:83], v96, s[8:9] offset:2048
	global_load_dwordx4 v[84:87], v97, s[8:9] offset:2048
	global_load_dwordx4 v[88:91], v98, s[8:9] offset:2048
	global_load_dwordx4 v[92:95], v99, s[8:9] offset:2048
	s_mul_i32 s6, s4, 0xc00
	v_add_u32_e32 v10, s6, v8
	s_lshl_b32 s7, s4, 5
	v_add_u32_e32 v11, s7, v205
	s_waitcnt vmcnt(8)
	v_lshlrev_b32_e32 v24, 16, v48
	v_and_b32_e32 v25, 0xffff0000, v48
	v_lshlrev_b32_e32 v26, 16, v49
	v_and_b32_e32 v27, 0xffff0000, v49
	v_lshlrev_b32_e32 v28, 16, v50
	v_and_b32_e32 v29, 0xffff0000, v50
	v_lshlrev_b32_e32 v30, 16, v51
	v_and_b32_e32 v31, 0xffff0000, v51
	v_pk_mul_f32 v[16:17], v[100:101], v[24:25]
	v_pk_mul_f32 v[18:19], v[102:103], v[26:27]
	v_pk_mul_f32 v[20:21], v[104:105], v[28:29]
	v_pk_mul_f32 v[22:23], v[106:107], v[30:31]
	v_lshlrev_b32_e32 v24, 16, v52
	v_and_b32_e32 v25, 0xffff0000, v52
	v_lshlrev_b32_e32 v26, 16, v53
	v_and_b32_e32 v27, 0xffff0000, v53
	v_lshlrev_b32_e32 v28, 16, v54
	v_and_b32_e32 v29, 0xffff0000, v54
	v_lshlrev_b32_e32 v30, 16, v55
	v_and_b32_e32 v31, 0xffff0000, v55
	v_pk_fma_f32 v[16:17], v[108:109], v[24:25], v[16:17]
	v_pk_fma_f32 v[18:19], v[110:111], v[26:27], v[18:19]
	v_pk_fma_f32 v[20:21], v[112:113], v[28:29], v[20:21]
	v_pk_fma_f32 v[22:23], v[114:115], v[30:31], v[22:23]
	v_lshlrev_b32_e32 v24, 16, v56
	v_and_b32_e32 v25, 0xffff0000, v56
	v_lshlrev_b32_e32 v26, 16, v57
	v_and_b32_e32 v27, 0xffff0000, v57
	v_lshlrev_b32_e32 v28, 16, v58
	v_and_b32_e32 v29, 0xffff0000, v58
	v_lshlrev_b32_e32 v30, 16, v59
	v_and_b32_e32 v31, 0xffff0000, v59
	v_pk_fma_f32 v[16:17], v[116:117], v[24:25], v[16:17]
	v_pk_fma_f32 v[18:19], v[118:119], v[26:27], v[18:19]
	v_pk_fma_f32 v[20:21], v[120:121], v[28:29], v[20:21]
	v_pk_fma_f32 v[22:23], v[122:123], v[30:31], v[22:23]
	v_lshlrev_b32_e32 v24, 16, v60
	v_and_b32_e32 v25, 0xffff0000, v60
	v_lshlrev_b32_e32 v26, 16, v61
	v_and_b32_e32 v27, 0xffff0000, v61
; __device__ __forceinline__ float bf2f(bf16_t h) { return __uint_as_float(((unsigned)h) << 16); }
; __device__ __forceinline__ float sigmoidf_(float x) { return __builtin_amdgcn_rcpf(1.f + __expf(-x)); }
; __device__ __forceinline__ float siluf_(float x) { return x * __builtin_amdgcn_rcpf(1.f + __expf(-x)); }
; __device__ __forceinline__ float softplus_acc(float x) { return x > 20.f ? x : log1pf(__expf(x)); }
; __device__ __forceinline__ void hyb_prep_phase(const Params& p, float* sm, int bid, int nb) {
;     ...
;     for (int g = 0; g < 12; g++) {
;       const int c = g * 128 + lane * 2;
;       float y0 = 0.f, y1 = 0.f;
; #pragma unroll
;       for (int j = 0; j < 4; j++) {
;         const unsigned u = *(const unsigned*)(z + (size_t)(row - 3 + j) * ZLD + 1536 + c);
;         const float2 w = *(const float2*)(p.hyb_conv + j * 1536 + c);
;         y0 += w.x * bf2f((bf16_t)(u & 0xffff));
;         y1 += w.y * bf2f((bf16_t)(u >> 16));
;       }
;       y[g][0] = siluf_(y0); y[g][1] = siluf_(y1);
;     }
; #pragma unroll
;     for (int g = 0; g < 8; g++) {
;       const float n2 = wave_sum_fast(y[g][0] * y[g][0] + y[g][1] * y[g][1]);
;       const float sc = rsqrtf(n2 + EPS);
;       y[g][0] *= sc; y[g][1] *= sc;
;     }
; #pragma unroll
;     for (int g = 0; g < 12; g++) *(unsigned*)(gp + (size_t)row * 1536 + g * 128 + lane * 2) = pack2(y[g][0], y[g][1]);
;     if (lane < 4) {
;       const float ga = zg[(size_t)row * 16 + 8 + lane], gb = zg[(size_t)row * 16 + 12 + lane];
;       gg[(size_t)row * 8 + lane] = -__expf(p.hyb_a_log[lane]) * softplus_acc(ga + p.hyb_dt_bias[lane]);
;       gg[(size_t)row * 8 + 4 + lane] = sigmoidf_(gb);
;     }
	v_lshlrev_b32_e32 v28, 16, v62
	v_and_b32_e32 v29, 0xffff0000, v62
	v_lshlrev_b32_e32 v30, 16, v63
	v_and_b32_e32 v31, 0xffff0000, v63
	v_pk_fma_f32 v[16:17], v[124:125], v[24:25], v[16:17]
	v_pk_fma_f32 v[18:19], v[126:127], v[26:27], v[18:19]
	v_pk_fma_f32 v[20:21], v[128:129], v[28:29], v[20:21]
	v_pk_fma_f32 v[22:23], v[130:131], v[30:31], v[22:23]
	v_add_f32_e32 v167, v160, v165
	v_mul_f32_e32 v46, 0xbfb8aa3b, v161
	v_mul_f32_e32 v204, 0x3fb8aa3b, v167
	v_exp_f32_e32 v46, v46
	v_exp_f32_e32 v204, v204
	s_nop 1
	v_add_f32_e32 v46, 1.0, v46
	v_add_f32_e32 v160, 1.0, v204
	v_rcp_f32_e32 v46, v46
	v_add_f32_e32 v161, -1.0, v160
	v_log_f32_e32 v160, v160
	v_cmp_eq_f32_e32 vcc, 0, v161
	v_rcp_f32_e32 v161, v161
	global_store_dword v11, v46, s[14:15] offset:16
	v_mul_f32_e32 v160, 0x3f317218, v160
	v_mul_f32_e32 v161, v161, v204
	v_mul_f32_e32 v160, v160, v161
	v_cndmask_b32_e32 v160, v160, v204, vcc
	v_cmp_lt_f32_e32 vcc, 0x41a00000, v167
	s_nop 1
	v_cndmask_b32_e32 v160, v160, v167, vcc
	v_mul_f32_e32 v160, v166, v160
	global_store_dword v11, v160, s[14:15]
	v_pk_mul_f32 v[32:33], v[16:17], s[18:19]
	v_pk_mul_f32 v[34:35], v[18:19], s[18:19]
	v_pk_mul_f32 v[36:37], v[20:21], s[18:19]
	v_pk_mul_f32 v[38:39], v[22:23], s[18:19]
	v_exp_f32_e32 v32, v32
	v_exp_f32_e32 v33, v33
	v_exp_f32_e32 v34, v34
	v_exp_f32_e32 v35, v35
	v_exp_f32_e32 v36, v36
	v_exp_f32_e32 v37, v37
	v_exp_f32_e32 v38, v38
	v_exp_f32_e32 v39, v39
	v_pk_add_f32 v[32:33], v[32:33], s[20:21]
	v_pk_add_f32 v[34:35], v[34:35], s[20:21]
	v_pk_add_f32 v[36:37], v[36:37], s[20:21]
	v_pk_add_f32 v[38:39], v[38:39], s[20:21]
	v_rcp_f32_e32 v32, v32
	v_rcp_f32_e32 v33, v33
	v_rcp_f32_e32 v34, v34
	v_rcp_f32_e32 v35, v35
	v_rcp_f32_e32 v36, v36
	v_rcp_f32_e32 v37, v37
	v_rcp_f32_e32 v38, v38
	v_rcp_f32_e32 v39, v39
	v_pk_mul_f32 v[16:17], v[16:17], v[32:33]
	v_pk_mul_f32 v[18:19], v[18:19], v[34:35]
	v_pk_mul_f32 v[20:21], v[20:21], v[36:37]
	v_pk_mul_f32 v[22:23], v[22:23], v[38:39]
	v_pk_mul_f32 v[40:41], v[16:17], v[16:17]
	v_pk_fma_f32 v[40:41], v[18:19], v[18:19], v[40:41]
	v_pk_fma_f32 v[40:41], v[20:21], v[20:21], v[40:41]
	v_pk_fma_f32 v[40:41], v[22:23], v[22:23], v[40:41]
	v_add_f32_e32 v42, v40, v41
	s_nop 1
	v_add_f32_dpp v42, v42, v42 quad_perm:[1,0,3,2] row_mask:0xf bank_mask:0xf bound_ctrl:1
	s_nop 1
	v_add_f32_dpp v42, v42, v42 quad_perm:[2,3,0,1] row_mask:0xf bank_mask:0xf bound_ctrl:1
	s_nop 1
	v_add_f32_dpp v42, v42, v42 row_half_mirror row_mask:0xf bank_mask:0xf bound_ctrl:1
	s_nop 1
	v_add_f32_dpp v42, v42, v42 row_mirror row_mask:0xf bank_mask:0xf bound_ctrl:1
	v_add_f32_e32 v42, 0x358637bd, v42
	v_rsq_f32_e32 v44, v42
	s_nop 1
	v_pk_mul_f32 v[16:17], v[16:17], v[44:45] op_sel_hi:[1,0]
	v_pk_mul_f32 v[18:19], v[18:19], v[44:45] op_sel_hi:[1,0]
	v_pk_mul_f32 v[20:21], v[20:21], v[44:45] op_sel_hi:[1,0]
	v_pk_mul_f32 v[22:23], v[22:23], v[44:45] op_sel_hi:[1,0]
	v_cvt_pk_bf16_f32 v12, v16, v17
	v_cvt_pk_bf16_f32 v13, v18, v19
	v_cvt_pk_bf16_f32 v14, v20, v21
	v_cvt_pk_bf16_f32 v15, v22, v23
	global_store_dwordx4 v10, v[12:15], s[10:11]
	s_waitcnt vmcnt(7)
	v_lshlrev_b32_e32 v24, 16, v64
	v_and_b32_e32 v25, 0xffff0000, v64
	v_lshlrev_b32_e32 v26, 16, v65
	v_and_b32_e32 v27, 0xffff0000, v65
	v_lshlrev_b32_e32 v28, 16, v66
	v_and_b32_e32 v29, 0xffff0000, v66
	v_lshlrev_b32_e32 v30, 16, v67
	v_and_b32_e32 v31, 0xffff0000, v67
	v_pk_mul_f32 v[16:17], v[132:133], v[24:25]
	v_pk_mul_f32 v[18:19], v[134:135], v[26:27]
	v_pk_mul_f32 v[20:21], v[136:137], v[28:29]
	v_pk_mul_f32 v[22:23], v[138:139], v[30:31]
	v_lshlrev_b32_e32 v24, 16, v68
	v_and_b32_e32 v25, 0xffff0000, v68
	v_lshlrev_b32_e32 v26, 16, v69
	v_and_b32_e32 v27, 0xffff0000, v69
	v_lshlrev_b32_e32 v28, 16, v70
	v_and_b32_e32 v29, 0xffff0000, v70
	v_lshlrev_b32_e32 v30, 16, v71
	v_and_b32_e32 v31, 0xffff0000, v71
	v_pk_fma_f32 v[16:17], v[140:141], v[24:25], v[16:17]
	v_pk_fma_f32 v[18:19], v[142:143], v[26:27], v[18:19]
	v_pk_fma_f32 v[20:21], v[144:145], v[28:29], v[20:21]
	v_pk_fma_f32 v[22:23], v[146:147], v[30:31], v[22:23]
	v_lshlrev_b32_e32 v24, 16, v72
	v_and_b32_e32 v25, 0xffff0000, v72
	v_lshlrev_b32_e32 v26, 16, v73
	v_and_b32_e32 v27, 0xffff0000, v73
	v_lshlrev_b32_e32 v28, 16, v74
	v_and_b32_e32 v29, 0xffff0000, v74
	v_lshlrev_b32_e32 v30, 16, v75
	v_and_b32_e32 v31, 0xffff0000, v75
	v_pk_fma_f32 v[16:17], v[148:149], v[24:25], v[16:17]
	v_pk_fma_f32 v[18:19], v[150:151], v[26:27], v[18:19]
	v_pk_fma_f32 v[20:21], v[152:153], v[28:29], v[20:21]
	v_pk_fma_f32 v[22:23], v[154:155], v[30:31], v[22:23]
	v_lshlrev_b32_e32 v24, 16, v76
	v_and_b32_e32 v25, 0xffff0000, v76
	v_lshlrev_b32_e32 v26, 16, v77
	v_and_b32_e32 v27, 0xffff0000, v77
	v_lshlrev_b32_e32 v28, 16, v78
	v_and_b32_e32 v29, 0xffff0000, v78
	v_lshlrev_b32_e32 v30, 16, v79
	v_and_b32_e32 v31, 0xffff0000, v79
	v_pk_fma_f32 v[16:17], v[156:157], v[24:25], v[16:17]
	v_pk_fma_f32 v[18:19], v[158:159], v[26:27], v[18:19]
	v_pk_fma_f32 v[20:21], v[168:169], v[28:29], v[20:21]
	v_pk_fma_f32 v[22:23], v[170:171], v[30:31], v[22:23]
	v_pk_mul_f32 v[32:33], v[16:17], s[18:19]
	v_pk_mul_f32 v[34:35], v[18:19], s[18:19]
	v_pk_mul_f32 v[36:37], v[20:21], s[18:19]
	v_pk_mul_f32 v[38:39], v[22:23], s[18:19]
	v_exp_f32_e32 v32, v32
	v_exp_f32_e32 v33, v33
	v_exp_f32_e32 v34, v34
	v_exp_f32_e32 v35, v35
	v_exp_f32_e32 v36, v36
	v_exp_f32_e32 v37, v37
	v_exp_f32_e32 v38, v38
	v_exp_f32_e32 v39, v39
	v_pk_add_f32 v[32:33], v[32:33], s[20:21]
	v_pk_add_f32 v[34:35], v[34:35], s[20:21]
	v_pk_add_f32 v[36:37], v[36:37], s[20:21]
	v_pk_add_f32 v[38:39], v[38:39], s[20:21]
	v_rcp_f32_e32 v32, v32
	v_rcp_f32_e32 v33, v33
	v_rcp_f32_e32 v34, v34
	v_rcp_f32_e32 v35, v35
	v_rcp_f32_e32 v36, v36
	v_rcp_f32_e32 v37, v37
	v_rcp_f32_e32 v38, v38
	v_rcp_f32_e32 v39, v39
	v_pk_mul_f32 v[16:17], v[16:17], v[32:33]
	v_pk_mul_f32 v[18:19], v[18:19], v[34:35]
	v_pk_mul_f32 v[20:21], v[20:21], v[36:37]
	v_pk_mul_f32 v[22:23], v[22:23], v[38:39]
	v_pk_mul_f32 v[40:41], v[16:17], v[16:17]
	v_pk_fma_f32 v[40:41], v[18:19], v[18:19], v[40:41]
	v_pk_fma_f32 v[40:41], v[20:21], v[20:21], v[40:41]
	v_pk_fma_f32 v[40:41], v[22:23], v[22:23], v[40:41]
	v_add_f32_e32 v42, v40, v41
	s_nop 1
	v_add_f32_dpp v42, v42, v42 quad_perm:[1,0,3,2] row_mask:0xf bank_mask:0xf bound_ctrl:1
	s_nop 1
	v_add_f32_dpp v42, v42, v42 quad_perm:[2,3,0,1] row_mask:0xf bank_mask:0xf bound_ctrl:1
	s_nop 1
	v_add_f32_dpp v42, v42, v42 row_half_mirror row_mask:0xf bank_mask:0xf bound_ctrl:1
	s_nop 1
	v_add_f32_dpp v42, v42, v42 row_mirror row_mask:0xf bank_mask:0xf bound_ctrl:1
	v_add_f32_e32 v42, 0x358637bd, v42
	v_rsq_f32_e32 v44, v42
	s_nop 1
	v_pk_mul_f32 v[16:17], v[16:17], v[44:45] op_sel_hi:[1,0]
	v_pk_mul_f32 v[18:19], v[18:19], v[44:45] op_sel_hi:[1,0]
	v_pk_mul_f32 v[20:21], v[20:21], v[44:45] op_sel_hi:[1,0]
	v_pk_mul_f32 v[22:23], v[22:23], v[44:45] op_sel_hi:[1,0]
	v_cvt_pk_bf16_f32 v12, v16, v17
	v_cvt_pk_bf16_f32 v13, v18, v19
	v_cvt_pk_bf16_f32 v14, v20, v21
	v_cvt_pk_bf16_f32 v15, v22, v23
	global_store_dwordx4 v10, v[12:15], s[10:11] offset:1024
	s_waitcnt vmcnt(4)
; __device__ __forceinline__ float bf2f(bf16_t h) { return __uint_as_float(((unsigned)h) << 16); }
; __device__ __forceinline__ float siluf_(float x) { return x * __builtin_amdgcn_rcpf(1.f + __expf(-x)); }
; __device__ __forceinline__ void hyb_prep_phase(const Params& p, float* sm, int bid, int nb) {
;     ...
;     for (int g = 0; g < 12; g++) {
;       const int c = g * 128 + lane * 2;
;       float y0 = 0.f, y1 = 0.f;
; #pragma unroll
;       for (int j = 0; j < 4; j++) {
;         const unsigned u = *(const unsigned*)(z + (size_t)(row - 3 + j) * ZLD + 1536 + c);
;         const float2 w = *(const float2*)(p.hyb_conv + j * 1536 + c);
;         y0 += w.x * bf2f((bf16_t)(u & 0xffff));
;         y1 += w.y * bf2f((bf16_t)(u >> 16));
;       }
;       y[g][0] = siluf_(y0); y[g][1] = siluf_(y1);
;     }
; #pragma unroll
;     for (int g = 0; g < 8; g++) {
;       const float n2 = wave_sum_fast(y[g][0] * y[g][0] + y[g][1] * y[g][1]);
;       const float sc = rsqrtf(n2 + EPS);
;       y[g][0] *= sc; y[g][1] *= sc;
;     }
; #pragma unroll
;     for (int g = 0; g < 12; g++) *(unsigned*)(gp + (size_t)row * 1536 + g * 128 + lane * 2) = pack2(y[g][0], y[g][1]);
	v_lshlrev_b32_e32 v24, 16, v80
	v_and_b32_e32 v25, 0xffff0000, v80
	v_lshlrev_b32_e32 v26, 16, v81
	v_and_b32_e32 v27, 0xffff0000, v81
	v_lshlrev_b32_e32 v28, 16, v82
	v_and_b32_e32 v29, 0xffff0000, v82
	v_lshlrev_b32_e32 v30, 16, v83
	v_and_b32_e32 v31, 0xffff0000, v83
	v_pk_mul_f32 v[16:17], v[172:173], v[24:25]
	v_pk_mul_f32 v[18:19], v[174:175], v[26:27]
	v_pk_mul_f32 v[20:21], v[176:177], v[28:29]
	v_pk_mul_f32 v[22:23], v[178:179], v[30:31]
	v_lshlrev_b32_e32 v24, 16, v84
	v_and_b32_e32 v25, 0xffff0000, v84
	v_lshlrev_b32_e32 v26, 16, v85
	v_and_b32_e32 v27, 0xffff0000, v85
	v_lshlrev_b32_e32 v28, 16, v86
	v_and_b32_e32 v29, 0xffff0000, v86
	v_lshlrev_b32_e32 v30, 16, v87
	v_and_b32_e32 v31, 0xffff0000, v87
	v_pk_fma_f32 v[16:17], v[180:181], v[24:25], v[16:17]
	v_pk_fma_f32 v[18:19], v[182:183], v[26:27], v[18:19]
	v_pk_fma_f32 v[20:21], v[184:185], v[28:29], v[20:21]
	v_pk_fma_f32 v[22:23], v[186:187], v[30:31], v[22:23]
	v_lshlrev_b32_e32 v24, 16, v88
	v_and_b32_e32 v25, 0xffff0000, v88
	v_lshlrev_b32_e32 v26, 16, v89
	v_and_b32_e32 v27, 0xffff0000, v89
	v_lshlrev_b32_e32 v28, 16, v90
	v_and_b32_e32 v29, 0xffff0000, v90
	v_lshlrev_b32_e32 v30, 16, v91
	v_and_b32_e32 v31, 0xffff0000, v91
	v_pk_fma_f32 v[16:17], v[188:189], v[24:25], v[16:17]
	v_pk_fma_f32 v[18:19], v[190:191], v[26:27], v[18:19]
	v_pk_fma_f32 v[20:21], v[192:193], v[28:29], v[20:21]
	v_pk_fma_f32 v[22:23], v[194:195], v[30:31], v[22:23]
	v_lshlrev_b32_e32 v24, 16, v92
	v_and_b32_e32 v25, 0xffff0000, v92
	v_lshlrev_b32_e32 v26, 16, v93
	v_and_b32_e32 v27, 0xffff0000, v93
	v_lshlrev_b32_e32 v28, 16, v94
	v_and_b32_e32 v29, 0xffff0000, v94
	v_lshlrev_b32_e32 v30, 16, v95
	v_and_b32_e32 v31, 0xffff0000, v95
	v_pk_fma_f32 v[16:17], v[196:197], v[24:25], v[16:17]
	v_pk_fma_f32 v[18:19], v[198:199], v[26:27], v[18:19]
	v_pk_fma_f32 v[20:21], v[200:201], v[28:29], v[20:21]
	v_pk_fma_f32 v[22:23], v[202:203], v[30:31], v[22:23]
	v_pk_mul_f32 v[32:33], v[16:17], s[18:19]
	v_pk_mul_f32 v[34:35], v[18:19], s[18:19]
	v_pk_mul_f32 v[36:37], v[20:21], s[18:19]
	v_pk_mul_f32 v[38:39], v[22:23], s[18:19]
	v_exp_f32_e32 v32, v32
	v_exp_f32_e32 v33, v33
	v_exp_f32_e32 v34, v34
	v_exp_f32_e32 v35, v35
	v_exp_f32_e32 v36, v36
	v_exp_f32_e32 v37, v37
	v_exp_f32_e32 v38, v38
	v_exp_f32_e32 v39, v39
	v_pk_add_f32 v[32:33], v[32:33], s[20:21]
	v_pk_add_f32 v[34:35], v[34:35], s[20:21]
	v_pk_add_f32 v[36:37], v[36:37], s[20:21]
	v_pk_add_f32 v[38:39], v[38:39], s[20:21]
	v_rcp_f32_e32 v32, v32
	v_rcp_f32_e32 v33, v33
	v_rcp_f32_e32 v34, v34
	v_rcp_f32_e32 v35, v35
	v_rcp_f32_e32 v36, v36
	v_rcp_f32_e32 v37, v37
	v_rcp_f32_e32 v38, v38
	v_rcp_f32_e32 v39, v39
	v_pk_mul_f32 v[16:17], v[16:17], v[32:33]
	v_pk_mul_f32 v[18:19], v[18:19], v[34:35]
	v_pk_mul_f32 v[20:21], v[20:21], v[36:37]
	v_pk_mul_f32 v[22:23], v[22:23], v[38:39]
	v_cvt_pk_bf16_f32 v12, v16, v17
	v_cvt_pk_bf16_f32 v13, v18, v19
	v_cvt_pk_bf16_f32 v14, v20, v21
	v_cvt_pk_bf16_f32 v15, v22, v23
	global_store_dwordx4 v10, v[12:15], s[10:11] offset:2048
.Lp5_next:
	s_add_i32 s4, s4, s16
	s_cmp_lt_u32 s4, 0x8200
	s_cbranch_scc1 .Lp5_row
	s_waitcnt vmcnt(0)
